# P6 epilogue: rsqrt denormal-range rescale removed (argument >= 1e-6 always; bit-identical)
# speedup vs baseline: 1.0055x; 1.0055x over previous
.LBB0_891:
	v_lshl_add_u32 v144, s6, 8, v152
	v_ashrrev_i32_e32 v145, 31, v144
	v_lshl_add_u64 v[150:151], v[144:145], 2, s[86:87]
	s_nop 0
	v_or_b32_e32 v162, 16, v144
	v_ashrrev_i32_e32 v163, 31, v162
	v_lshl_add_u64 v[164:165], v[162:163], 2, s[86:87]
	v_lshl_or_b32 v148, s7, 7, v154
	v_readlane_b32 s6, v246, 36
	v_readlane_b32 s7, v246, 37
	v_ashrrev_i32_e32 v149, 31, v148
	v_lshlrev_b64 v[148:149], 1, v[148:149]
	v_mov_b64_e32 v[146:147], s[6:7]
	v_mad_i64_i32 v[160:161], s[6:7], v144, s45, v[146:147]
	v_lshl_add_u64 v[160:161], v[160:161], 0, v[148:149]
	v_fmamk_f32 v145, v229, 0x3a000000, v158
	v_rsq_f32_e32 v145, v145
	s_nop 0
	v_mov_b32_e32 v166, v145
	v_pk_mul_f32 v[124:125], v[124:125], v[166:167] op_sel_hi:[1,0]
	v_pk_mul_f32 v[126:127], v[126:127], v[166:167] op_sel_hi:[1,0]
	v_pk_mul_f32 v[120:121], v[120:121], v[166:167] op_sel_hi:[1,0]
	v_pk_mul_f32 v[122:123], v[122:123], v[166:167] op_sel_hi:[1,0]
	v_pk_mul_f32 v[116:117], v[116:117], v[166:167] op_sel_hi:[1,0]
	v_pk_mul_f32 v[118:119], v[118:119], v[166:167] op_sel_hi:[1,0]
	v_pk_mul_f32 v[112:113], v[112:113], v[166:167] op_sel_hi:[1,0]
	v_pk_mul_f32 v[114:115], v[114:115], v[166:167] op_sel_hi:[1,0]
	v_mul_f32_e32 v145, 0xbfb8aa3b, v124
	v_mul_f32_e32 v159, 0xbfb8aa3b, v125
	v_mul_f32_e32 v163, 0xbfb8aa3b, v126
	v_mul_f32_e32 v166, 0xbfb8aa3b, v127
	v_mul_f32_e32 v167, 0xbfb8aa3b, v120
	v_mul_f32_e32 v168, 0xbfb8aa3b, v121
	v_mul_f32_e32 v169, 0xbfb8aa3b, v122
	v_mul_f32_e32 v170, 0xbfb8aa3b, v123
	v_exp_f32_e32 v145, v145
	v_exp_f32_e32 v159, v159
	v_exp_f32_e32 v163, v163
	v_exp_f32_e32 v166, v166
	v_exp_f32_e32 v167, v167
	v_exp_f32_e32 v168, v168
	v_exp_f32_e32 v169, v169
	v_exp_f32_e32 v170, v170
	v_add_f32_e32 v145, 1.0, v145
	v_add_f32_e32 v159, 1.0, v159
	v_add_f32_e32 v163, 1.0, v163
	v_add_f32_e32 v171, 1.0, v166
	v_add_f32_e32 v172, 1.0, v167
	v_add_f32_e32 v173, 1.0, v168
	v_add_f32_e32 v174, 1.0, v169
	v_add_f32_e32 v175, 1.0, v170
	v_rcp_f32_e32 v166, v145
	v_rcp_f32_e32 v167, v159
	v_rcp_f32_e32 v168, v163
	v_rcp_f32_e32 v169, v171
	v_rcp_f32_e32 v170, v172
	v_rcp_f32_e32 v171, v173
	v_rcp_f32_e32 v172, v174
	v_rcp_f32_e32 v173, v175
	v_pk_mul_f32 v[124:125], v[124:125], v[166:167]
	v_pk_mul_f32 v[126:127], v[126:127], v[168:169]
	v_pk_mul_f32 v[120:121], v[120:121], v[170:171]
	v_pk_mul_f32 v[122:123], v[122:123], v[172:173]
	v_pk_mul_f32 v[116:117], v[116:117], v[124:125]
	v_pk_mul_f32 v[118:119], v[118:119], v[126:127]
	v_pk_mul_f32 v[120:121], v[112:113], v[120:121]
	v_pk_mul_f32 v[122:123], v[114:115], v[122:123]
	v_cvt_pk_bf16_f32 v112, v116, v117
	v_cvt_pk_bf16_f32 v113, v118, v119
	v_cvt_pk_bf16_f32 v114, v120, v121
	v_cvt_pk_bf16_f32 v115, v122, v123
	global_store_dwordx4 v[160:161], v[112:115], off nt
	s_nop 0
	s_nop 0
	v_or_b32_e32 v112, 32, v144
	v_mad_i64_i32 v[114:115], s[6:7], v162, s45, v[146:147]
	v_lshl_add_u64 v[114:115], v[114:115], 0, v[148:149]
	v_fmamk_f32 v113, v230, 0x3a000000, v158
	v_rsq_f32_e32 v118, v113
	v_ashrrev_i32_e32 v113, 31, v112
	v_lshl_add_u64 v[116:117], v[112:113], 2, s[86:87]
	v_pk_mul_f32 v[108:109], v[108:109], v[118:119] op_sel_hi:[1,0]
	v_pk_mul_f32 v[110:111], v[110:111], v[118:119] op_sel_hi:[1,0]
	v_pk_mul_f32 v[104:105], v[104:105], v[118:119] op_sel_hi:[1,0]
	v_pk_mul_f32 v[106:107], v[106:107], v[118:119] op_sel_hi:[1,0]
	v_pk_mul_f32 v[100:101], v[100:101], v[118:119] op_sel_hi:[1,0]
	v_pk_mul_f32 v[102:103], v[102:103], v[118:119] op_sel_hi:[1,0]
	v_pk_mul_f32 v[96:97], v[96:97], v[118:119] op_sel_hi:[1,0]
	v_pk_mul_f32 v[98:99], v[98:99], v[118:119] op_sel_hi:[1,0]
	v_mul_f32_e32 v113, 0xbfb8aa3b, v108
	v_mul_f32_e32 v118, 0xbfb8aa3b, v109
	v_mul_f32_e32 v119, 0xbfb8aa3b, v110
	v_mul_f32_e32 v120, 0xbfb8aa3b, v111
	v_mul_f32_e32 v121, 0xbfb8aa3b, v104
	v_mul_f32_e32 v122, 0xbfb8aa3b, v105
	v_mul_f32_e32 v123, 0xbfb8aa3b, v106
	v_mul_f32_e32 v124, 0xbfb8aa3b, v107
	v_exp_f32_e32 v113, v113
	v_exp_f32_e32 v118, v118
	v_exp_f32_e32 v119, v119
	v_exp_f32_e32 v120, v120
	v_exp_f32_e32 v121, v121
	v_exp_f32_e32 v122, v122
	v_exp_f32_e32 v123, v123
	v_exp_f32_e32 v124, v124
	v_add_f32_e32 v113, 1.0, v113
	v_add_f32_e32 v125, 1.0, v118
	v_add_f32_e32 v126, 1.0, v119
	v_add_f32_e32 v127, 1.0, v120
	v_add_f32_e32 v145, 1.0, v121
	v_add_f32_e32 v159, 1.0, v122
	v_add_f32_e32 v160, 1.0, v123
	v_add_f32_e32 v161, 1.0, v124
	v_rcp_f32_e32 v118, v113
	v_rcp_f32_e32 v119, v125
	v_rcp_f32_e32 v120, v126
	v_rcp_f32_e32 v121, v127
	v_rcp_f32_e32 v122, v145
	v_rcp_f32_e32 v123, v159
	v_rcp_f32_e32 v124, v160
	v_rcp_f32_e32 v125, v161
	v_pk_mul_f32 v[108:109], v[108:109], v[118:119]
	v_pk_mul_f32 v[110:111], v[110:111], v[120:121]
	v_pk_mul_f32 v[104:105], v[104:105], v[122:123]
	v_pk_mul_f32 v[106:107], v[106:107], v[124:125]
	v_pk_mul_f32 v[100:101], v[100:101], v[108:109]
	v_pk_mul_f32 v[102:103], v[102:103], v[110:111]
	v_pk_mul_f32 v[104:105], v[96:97], v[104:105]
	v_pk_mul_f32 v[106:107], v[98:99], v[106:107]
	v_cvt_pk_bf16_f32 v96, v100, v101
	v_cvt_pk_bf16_f32 v97, v102, v103
	v_cvt_pk_bf16_f32 v98, v104, v105
	v_cvt_pk_bf16_f32 v99, v106, v107
	global_store_dwordx4 v[114:115], v[96:99], off nt
	s_nop 0
	s_nop 0
	v_or_b32_e32 v96, 48, v144
	v_mad_i64_i32 v[98:99], s[6:7], v112, s45, v[146:147]
	v_lshl_add_u64 v[98:99], v[98:99], 0, v[148:149]
	v_fmamk_f32 v97, v231, 0x3a000000, v158
	v_rsq_f32_e32 v102, v97
	v_ashrrev_i32_e32 v97, 31, v96
	v_lshl_add_u64 v[100:101], v[96:97], 2, s[86:87]
	v_pk_mul_f32 v[92:93], v[92:93], v[102:103] op_sel_hi:[1,0]
	v_pk_mul_f32 v[94:95], v[94:95], v[102:103] op_sel_hi:[1,0]
	v_pk_mul_f32 v[88:89], v[88:89], v[102:103] op_sel_hi:[1,0]
	v_pk_mul_f32 v[90:91], v[90:91], v[102:103] op_sel_hi:[1,0]
	v_pk_mul_f32 v[84:85], v[84:85], v[102:103] op_sel_hi:[1,0]
	v_pk_mul_f32 v[86:87], v[86:87], v[102:103] op_sel_hi:[1,0]
	v_pk_mul_f32 v[80:81], v[80:81], v[102:103] op_sel_hi:[1,0]
	v_pk_mul_f32 v[82:83], v[82:83], v[102:103] op_sel_hi:[1,0]
	v_mul_f32_e32 v97, 0xbfb8aa3b, v92
	v_mul_f32_e32 v102, 0xbfb8aa3b, v93
	v_mul_f32_e32 v103, 0xbfb8aa3b, v94
	v_mul_f32_e32 v104, 0xbfb8aa3b, v95
	v_mul_f32_e32 v105, 0xbfb8aa3b, v88
	v_mul_f32_e32 v106, 0xbfb8aa3b, v89
	v_mul_f32_e32 v107, 0xbfb8aa3b, v90
	v_mul_f32_e32 v108, 0xbfb8aa3b, v91
	v_exp_f32_e32 v97, v97
	v_exp_f32_e32 v102, v102
	v_exp_f32_e32 v103, v103
	v_exp_f32_e32 v104, v104
	v_exp_f32_e32 v105, v105
	v_exp_f32_e32 v106, v106
	v_exp_f32_e32 v107, v107
	v_exp_f32_e32 v108, v108
	v_add_f32_e32 v97, 1.0, v97
	v_add_f32_e32 v109, 1.0, v102
	v_add_f32_e32 v110, 1.0, v103
	v_add_f32_e32 v111, 1.0, v104
	v_add_f32_e32 v112, 1.0, v105
	v_add_f32_e32 v113, 1.0, v106
	v_add_f32_e32 v114, 1.0, v107
	v_add_f32_e32 v115, 1.0, v108
	v_rcp_f32_e32 v102, v97
	v_rcp_f32_e32 v103, v109
	v_rcp_f32_e32 v104, v110
	v_rcp_f32_e32 v105, v111
	v_rcp_f32_e32 v106, v112
	v_rcp_f32_e32 v107, v113
	v_rcp_f32_e32 v108, v114
	v_rcp_f32_e32 v109, v115
	v_pk_mul_f32 v[92:93], v[92:93], v[102:103]
	v_pk_mul_f32 v[94:95], v[94:95], v[104:105]
	v_pk_mul_f32 v[88:89], v[88:89], v[106:107]
	v_pk_mul_f32 v[90:91], v[90:91], v[108:109]
	v_pk_mul_f32 v[84:85], v[84:85], v[92:93]
	v_pk_mul_f32 v[86:87], v[86:87], v[94:95]
	v_pk_mul_f32 v[88:89], v[80:81], v[88:89]
	v_pk_mul_f32 v[90:91], v[82:83], v[90:91]
	v_cvt_pk_bf16_f32 v80, v84, v85
	v_cvt_pk_bf16_f32 v81, v86, v87
	v_cvt_pk_bf16_f32 v82, v88, v89
	v_cvt_pk_bf16_f32 v83, v90, v91
	global_store_dwordx4 v[98:99], v[80:83], off nt
	s_nop 1
	v_fmamk_f32 v80, v232, 0x3a000000, v158
	v_rsq_f32_e32 v82, v80
	v_mad_i64_i32 v[80:81], s[6:7], v96, s45, v[146:147]
	v_lshl_add_u64 v[80:81], v[80:81], 0, v[148:149]
	v_pk_mul_f32 v[76:77], v[76:77], v[82:83] op_sel_hi:[1,0]
	v_pk_mul_f32 v[78:79], v[78:79], v[82:83] op_sel_hi:[1,0]
	v_pk_mul_f32 v[72:73], v[72:73], v[82:83] op_sel_hi:[1,0]
	v_pk_mul_f32 v[74:75], v[74:75], v[82:83] op_sel_hi:[1,0]
	v_pk_mul_f32 v[68:69], v[68:69], v[82:83] op_sel_hi:[1,0]
	v_pk_mul_f32 v[70:71], v[70:71], v[82:83] op_sel_hi:[1,0]
	v_pk_mul_f32 v[64:65], v[64:65], v[82:83] op_sel_hi:[1,0]
	v_pk_mul_f32 v[66:67], v[66:67], v[82:83] op_sel_hi:[1,0]
	v_mul_f32_e32 v82, 0xbfb8aa3b, v76
	v_mul_f32_e32 v83, 0xbfb8aa3b, v77
	v_mul_f32_e32 v84, 0xbfb8aa3b, v78
	v_mul_f32_e32 v85, 0xbfb8aa3b, v79
	v_mul_f32_e32 v86, 0xbfb8aa3b, v72
	v_mul_f32_e32 v87, 0xbfb8aa3b, v73
	v_mul_f32_e32 v88, 0xbfb8aa3b, v74
	v_mul_f32_e32 v89, 0xbfb8aa3b, v75
	v_exp_f32_e32 v82, v82
	v_exp_f32_e32 v83, v83
	v_exp_f32_e32 v84, v84
	v_exp_f32_e32 v85, v85
	v_exp_f32_e32 v86, v86
	v_exp_f32_e32 v87, v87
	v_exp_f32_e32 v88, v88
	v_exp_f32_e32 v89, v89
	v_add_f32_e32 v82, 1.0, v82
	v_add_f32_e32 v83, 1.0, v83
	v_add_f32_e32 v84, 1.0, v84
	v_add_f32_e32 v85, 1.0, v85
	v_add_f32_e32 v86, 1.0, v86
	v_add_f32_e32 v87, 1.0, v87
	v_add_f32_e32 v88, 1.0, v88
	v_add_f32_e32 v89, 1.0, v89
	v_rcp_f32_e32 v82, v82
	v_rcp_f32_e32 v83, v83
	v_rcp_f32_e32 v84, v84
	v_rcp_f32_e32 v85, v85
	v_rcp_f32_e32 v86, v86
	v_rcp_f32_e32 v87, v87
	v_rcp_f32_e32 v88, v88
	v_rcp_f32_e32 v89, v89
	v_pk_mul_f32 v[76:77], v[76:77], v[82:83]
	v_pk_mul_f32 v[78:79], v[78:79], v[84:85]
	v_pk_mul_f32 v[72:73], v[72:73], v[86:87]
	v_pk_mul_f32 v[74:75], v[74:75], v[88:89]
	v_pk_mul_f32 v[68:69], v[68:69], v[76:77]
	v_pk_mul_f32 v[70:71], v[70:71], v[78:79]
	v_pk_mul_f32 v[72:73], v[64:65], v[72:73]
	v_pk_mul_f32 v[74:75], v[66:67], v[74:75]
	v_cvt_pk_bf16_f32 v64, v68, v69
	v_cvt_pk_bf16_f32 v65, v70, v71
	v_cvt_pk_bf16_f32 v66, v72, v73
	v_cvt_pk_bf16_f32 v67, v74, v75
	global_store_dwordx4 v[80:81], v[64:67], off nt
	s_nop 0
	s_nop 0
	v_add_u32_e32 v65, 0x80, v144
	v_fmamk_f32 v64, v233, 0x3a000000, v158
	v_rsq_f32_e32 v66, v64
	v_mad_i64_i32 v[64:65], s[6:7], v65, s45, v[146:147]
	v_lshl_add_u64 v[64:65], v[64:65], 0, v[148:149]
	v_pk_mul_f32 v[60:61], v[60:61], v[66:67] op_sel_hi:[1,0]
	v_pk_mul_f32 v[62:63], v[62:63], v[66:67] op_sel_hi:[1,0]
	v_pk_mul_f32 v[56:57], v[56:57], v[66:67] op_sel_hi:[1,0]
	v_pk_mul_f32 v[58:59], v[58:59], v[66:67] op_sel_hi:[1,0]
	v_pk_mul_f32 v[52:53], v[52:53], v[66:67] op_sel_hi:[1,0]
	v_pk_mul_f32 v[54:55], v[54:55], v[66:67] op_sel_hi:[1,0]
	v_pk_mul_f32 v[48:49], v[48:49], v[66:67] op_sel_hi:[1,0]
	v_pk_mul_f32 v[50:51], v[50:51], v[66:67] op_sel_hi:[1,0]
	v_mul_f32_e32 v66, 0xbfb8aa3b, v60
	v_mul_f32_e32 v67, 0xbfb8aa3b, v61
	v_mul_f32_e32 v68, 0xbfb8aa3b, v62
	v_mul_f32_e32 v69, 0xbfb8aa3b, v63
	v_mul_f32_e32 v70, 0xbfb8aa3b, v56
	v_mul_f32_e32 v71, 0xbfb8aa3b, v57
	v_mul_f32_e32 v72, 0xbfb8aa3b, v58
	v_mul_f32_e32 v73, 0xbfb8aa3b, v59
	v_exp_f32_e32 v66, v66
	v_exp_f32_e32 v67, v67
	v_exp_f32_e32 v68, v68
	v_exp_f32_e32 v69, v69
	v_exp_f32_e32 v70, v70
	v_exp_f32_e32 v71, v71
	v_exp_f32_e32 v72, v72
	v_exp_f32_e32 v73, v73
	v_add_f32_e32 v66, 1.0, v66
	v_add_f32_e32 v67, 1.0, v67
	v_add_f32_e32 v68, 1.0, v68
	v_add_f32_e32 v69, 1.0, v69
	v_add_f32_e32 v70, 1.0, v70
	v_add_f32_e32 v71, 1.0, v71
	v_add_f32_e32 v72, 1.0, v72
	v_add_f32_e32 v73, 1.0, v73
	v_rcp_f32_e32 v66, v66
	v_rcp_f32_e32 v67, v67
	v_rcp_f32_e32 v68, v68
	v_rcp_f32_e32 v69, v69
	v_rcp_f32_e32 v70, v70
	v_rcp_f32_e32 v71, v71
	v_rcp_f32_e32 v72, v72
	v_rcp_f32_e32 v73, v73
	v_pk_mul_f32 v[60:61], v[60:61], v[66:67]
	v_pk_mul_f32 v[62:63], v[62:63], v[68:69]
	v_pk_mul_f32 v[56:57], v[56:57], v[70:71]
	v_pk_mul_f32 v[58:59], v[58:59], v[72:73]
	v_pk_mul_f32 v[52:53], v[52:53], v[60:61]
	v_pk_mul_f32 v[54:55], v[54:55], v[62:63]
	v_pk_mul_f32 v[56:57], v[48:49], v[56:57]
	v_pk_mul_f32 v[58:59], v[50:51], v[58:59]
	v_cvt_pk_bf16_f32 v48, v52, v53
	v_cvt_pk_bf16_f32 v49, v54, v55
	v_cvt_pk_bf16_f32 v50, v56, v57
	v_cvt_pk_bf16_f32 v51, v58, v59
	global_store_dwordx4 v[64:65], v[48:51], off nt
	s_nop 0
	s_nop 0
	v_add_u32_e32 v49, 0x90, v144
	v_fmamk_f32 v48, v234, 0x3a000000, v158
	v_rsq_f32_e32 v50, v48
	v_mad_i64_i32 v[48:49], s[6:7], v49, s45, v[146:147]
	v_lshl_add_u64 v[48:49], v[48:49], 0, v[148:149]
	v_pk_mul_f32 v[44:45], v[44:45], v[50:51] op_sel_hi:[1,0]
	v_pk_mul_f32 v[46:47], v[46:47], v[50:51] op_sel_hi:[1,0]
	v_pk_mul_f32 v[40:41], v[40:41], v[50:51] op_sel_hi:[1,0]
	v_pk_mul_f32 v[42:43], v[42:43], v[50:51] op_sel_hi:[1,0]
	v_pk_mul_f32 v[36:37], v[36:37], v[50:51] op_sel_hi:[1,0]
	v_pk_mul_f32 v[38:39], v[38:39], v[50:51] op_sel_hi:[1,0]
	v_pk_mul_f32 v[32:33], v[32:33], v[50:51] op_sel_hi:[1,0]
	v_pk_mul_f32 v[34:35], v[34:35], v[50:51] op_sel_hi:[1,0]
	v_mul_f32_e32 v50, 0xbfb8aa3b, v44
	v_mul_f32_e32 v51, 0xbfb8aa3b, v45
	v_mul_f32_e32 v52, 0xbfb8aa3b, v46
	v_mul_f32_e32 v53, 0xbfb8aa3b, v47
	v_mul_f32_e32 v54, 0xbfb8aa3b, v40
	v_mul_f32_e32 v55, 0xbfb8aa3b, v41
	v_mul_f32_e32 v56, 0xbfb8aa3b, v42
	v_mul_f32_e32 v57, 0xbfb8aa3b, v43
	v_exp_f32_e32 v50, v50
	v_exp_f32_e32 v51, v51
	v_exp_f32_e32 v52, v52
	v_exp_f32_e32 v53, v53
	v_exp_f32_e32 v54, v54
	v_exp_f32_e32 v55, v55
	v_exp_f32_e32 v56, v56
	v_exp_f32_e32 v57, v57
	v_add_f32_e32 v50, 1.0, v50
	v_add_f32_e32 v51, 1.0, v51
	v_add_f32_e32 v52, 1.0, v52
	v_add_f32_e32 v53, 1.0, v53
	v_add_f32_e32 v54, 1.0, v54
	v_add_f32_e32 v55, 1.0, v55
	v_add_f32_e32 v56, 1.0, v56
	v_add_f32_e32 v57, 1.0, v57
	v_rcp_f32_e32 v50, v50
	v_rcp_f32_e32 v51, v51
	v_rcp_f32_e32 v52, v52
	v_rcp_f32_e32 v53, v53
	v_rcp_f32_e32 v54, v54
	v_rcp_f32_e32 v55, v55
	v_rcp_f32_e32 v56, v56
	v_rcp_f32_e32 v57, v57
	v_pk_mul_f32 v[44:45], v[44:45], v[50:51]
	v_pk_mul_f32 v[46:47], v[46:47], v[52:53]
	v_pk_mul_f32 v[40:41], v[40:41], v[54:55]
	v_pk_mul_f32 v[42:43], v[42:43], v[56:57]
	v_pk_mul_f32 v[36:37], v[36:37], v[44:45]
	v_pk_mul_f32 v[38:39], v[38:39], v[46:47]
	v_pk_mul_f32 v[40:41], v[32:33], v[40:41]
	v_pk_mul_f32 v[42:43], v[34:35], v[42:43]
	v_cvt_pk_bf16_f32 v32, v36, v37
	v_cvt_pk_bf16_f32 v33, v38, v39
	v_cvt_pk_bf16_f32 v34, v40, v41
	v_cvt_pk_bf16_f32 v35, v42, v43
	global_store_dwordx4 v[48:49], v[32:35], off nt
	s_nop 0
	s_nop 0
	v_add_u32_e32 v33, 0xa0, v144
	v_fmamk_f32 v32, v235, 0x3a000000, v158
	v_rsq_f32_e32 v34, v32
	v_mad_i64_i32 v[32:33], s[6:7], v33, s45, v[146:147]
	v_lshl_add_u64 v[32:33], v[32:33], 0, v[148:149]
	v_pk_mul_f32 v[28:29], v[28:29], v[34:35] op_sel_hi:[1,0]
	v_pk_mul_f32 v[30:31], v[30:31], v[34:35] op_sel_hi:[1,0]
	v_pk_mul_f32 v[24:25], v[24:25], v[34:35] op_sel_hi:[1,0]
	v_pk_mul_f32 v[26:27], v[26:27], v[34:35] op_sel_hi:[1,0]
	v_pk_mul_f32 v[20:21], v[20:21], v[34:35] op_sel_hi:[1,0]
	v_pk_mul_f32 v[22:23], v[22:23], v[34:35] op_sel_hi:[1,0]
	v_pk_mul_f32 v[16:17], v[16:17], v[34:35] op_sel_hi:[1,0]
	v_pk_mul_f32 v[18:19], v[18:19], v[34:35] op_sel_hi:[1,0]
	v_mul_f32_e32 v34, 0xbfb8aa3b, v28
	v_mul_f32_e32 v35, 0xbfb8aa3b, v29
	v_mul_f32_e32 v36, 0xbfb8aa3b, v30
	v_mul_f32_e32 v37, 0xbfb8aa3b, v31
	v_mul_f32_e32 v38, 0xbfb8aa3b, v24
	v_mul_f32_e32 v39, 0xbfb8aa3b, v25
	v_mul_f32_e32 v40, 0xbfb8aa3b, v26
	v_mul_f32_e32 v41, 0xbfb8aa3b, v27
	v_exp_f32_e32 v34, v34
	v_exp_f32_e32 v35, v35
	v_exp_f32_e32 v36, v36
	v_exp_f32_e32 v37, v37
	v_exp_f32_e32 v38, v38
	v_exp_f32_e32 v39, v39
	v_exp_f32_e32 v40, v40
	v_exp_f32_e32 v41, v41
	v_add_f32_e32 v34, 1.0, v34
	v_add_f32_e32 v35, 1.0, v35
	v_add_f32_e32 v36, 1.0, v36
	v_add_f32_e32 v37, 1.0, v37
	v_add_f32_e32 v38, 1.0, v38
	v_add_f32_e32 v39, 1.0, v39
	v_add_f32_e32 v40, 1.0, v40
	v_add_f32_e32 v41, 1.0, v41
	v_rcp_f32_e32 v34, v34
	v_rcp_f32_e32 v35, v35
	v_rcp_f32_e32 v36, v36
	v_rcp_f32_e32 v37, v37
	v_rcp_f32_e32 v38, v38
	v_rcp_f32_e32 v39, v39
	v_rcp_f32_e32 v40, v40
	v_rcp_f32_e32 v41, v41
	v_pk_mul_f32 v[28:29], v[28:29], v[34:35]
	v_pk_mul_f32 v[30:31], v[30:31], v[36:37]
	v_pk_mul_f32 v[24:25], v[24:25], v[38:39]
	v_pk_mul_f32 v[26:27], v[26:27], v[40:41]
	v_pk_mul_f32 v[20:21], v[20:21], v[28:29]
	v_pk_mul_f32 v[22:23], v[22:23], v[30:31]
	v_pk_mul_f32 v[24:25], v[16:17], v[24:25]
	v_pk_mul_f32 v[26:27], v[18:19], v[26:27]
	v_cvt_pk_bf16_f32 v16, v20, v21
	v_cvt_pk_bf16_f32 v17, v22, v23
	v_cvt_pk_bf16_f32 v18, v24, v25
	v_cvt_pk_bf16_f32 v19, v26, v27
	global_store_dwordx4 v[32:33], v[16:19], off nt
	s_nop 0
	s_andn2_b64 vcc, exec, s[4:5]
	v_add_u32_e32 v17, 0xb0, v144
	s_mov_b64 s[4:5], -1
	v_fmamk_f32 v16, v236, 0x3a000000, v158
	v_rsq_f32_e32 v18, v16
	v_mad_i64_i32 v[16:17], s[10:11], v17, s45, v[146:147]
	v_lshl_add_u64 v[16:17], v[16:17], 0, v[148:149]
	v_pk_mul_f32 v[12:13], v[12:13], v[18:19] op_sel_hi:[1,0]
	v_pk_mul_f32 v[14:15], v[14:15], v[18:19] op_sel_hi:[1,0]
	v_pk_mul_f32 v[8:9], v[8:9], v[18:19] op_sel_hi:[1,0]
	v_pk_mul_f32 v[10:11], v[10:11], v[18:19] op_sel_hi:[1,0]
	v_pk_mul_f32 v[4:5], v[4:5], v[18:19] op_sel_hi:[1,0]
	v_pk_mul_f32 v[6:7], v[6:7], v[18:19] op_sel_hi:[1,0]
	v_pk_mul_f32 v[0:1], v[0:1], v[18:19] op_sel_hi:[1,0]
	v_pk_mul_f32 v[2:3], v[2:3], v[18:19] op_sel_hi:[1,0]
	v_mul_f32_e32 v18, 0xbfb8aa3b, v12
	v_mul_f32_e32 v19, 0xbfb8aa3b, v13
	v_mul_f32_e32 v20, 0xbfb8aa3b, v14
	v_mul_f32_e32 v21, 0xbfb8aa3b, v15
	v_mul_f32_e32 v22, 0xbfb8aa3b, v8
	v_mul_f32_e32 v23, 0xbfb8aa3b, v9
	v_mul_f32_e32 v24, 0xbfb8aa3b, v10
	v_mul_f32_e32 v25, 0xbfb8aa3b, v11
	v_exp_f32_e32 v18, v18
	v_exp_f32_e32 v19, v19
	v_exp_f32_e32 v20, v20
	v_exp_f32_e32 v21, v21
	v_exp_f32_e32 v22, v22
	v_exp_f32_e32 v23, v23
	v_exp_f32_e32 v24, v24
	v_exp_f32_e32 v25, v25
	v_add_f32_e32 v18, 1.0, v18
	v_add_f32_e32 v19, 1.0, v19
	v_add_f32_e32 v20, 1.0, v20
	v_add_f32_e32 v21, 1.0, v21
	v_add_f32_e32 v22, 1.0, v22
	v_add_f32_e32 v23, 1.0, v23
	v_add_f32_e32 v24, 1.0, v24
	v_add_f32_e32 v25, 1.0, v25
	v_rcp_f32_e32 v18, v18
	v_rcp_f32_e32 v19, v19
	v_rcp_f32_e32 v20, v20
	v_rcp_f32_e32 v21, v21
	v_rcp_f32_e32 v22, v22
	v_rcp_f32_e32 v23, v23
	v_rcp_f32_e32 v24, v24
	v_rcp_f32_e32 v25, v25
	v_pk_mul_f32 v[12:13], v[12:13], v[18:19]
	v_pk_mul_f32 v[14:15], v[14:15], v[20:21]
	v_pk_mul_f32 v[8:9], v[8:9], v[22:23]
	v_pk_mul_f32 v[10:11], v[10:11], v[24:25]
	v_pk_mul_f32 v[4:5], v[4:5], v[12:13]
	v_pk_mul_f32 v[6:7], v[6:7], v[14:15]
	v_pk_mul_f32 v[8:9], v[0:1], v[8:9]
	v_pk_mul_f32 v[10:11], v[2:3], v[10:11]
	v_cvt_pk_bf16_f32 v0, v4, v5
	v_cvt_pk_bf16_f32 v1, v6, v7
	v_cvt_pk_bf16_f32 v2, v8, v9
	v_cvt_pk_bf16_f32 v3, v10, v11
	global_store_dwordx4 v[16:17], v[0:3], off nt
	s_cbranch_vccnz .LBB0_884
	s_andn2_b64 vcc, exec, s[0:1]
	s_cbranch_vccnz .LBB0_883
	s_barrier
	s_branch .LBB0_883
